# first grid barrier one-time residency count: 16 counter loads in flight instead of one at a time (on top of nt hints)
# baseline (speedup 1.0000x reference)
; __device__ __forceinline__ unsigned xb_ld(unsigned* p)              { return __hip_atomic_load(p, __ATOMIC_RELAXED, __HIP_MEMORY_SCOPE_AGENT); }
; __device__ __forceinline__ void xcd_barrier_complete(unsigned* bar, unsigned x, unsigned& nloc, unsigned& nx) {
;     const unsigned G = gridDim.x * gridDim.y * gridDim.z;
;     unsigned sum, cnt, mine, sp = 0u;
;     for (;;) {
;         sum = 0u; cnt = 0u; mine = 0u;
; #pragma unroll
;         for (unsigned j = 0; j < 16; ++j) { const unsigned c = xb_ld(&bar[XB_XCNT(j)]); sum += c; cnt += (c > 0u) ? 1u : 0u; mine = (j == x) ? c : mine; }
;         if (sum == G) break;
;         __builtin_amdgcn_s_sleep(1);
;         if ((++sp & 255u) == 0u) { if (xb_ld(&bar[XB_TMO])) break; if (sp > XB_SPIN_CAP) { atomicAdd(&bar[XB_TMO], 1u); break; } }
;     }
.LBB0_156:
	v_readlane_b32 s10, v251, 10
	v_readlane_b32 s8, v251, 13
	v_readlane_b32 s9, v251, 14
	s_nop 4
	global_load_dword v0, v1, s[8:9] sc1
	v_readlane_b32 s8, v251, 15
	v_readlane_b32 s9, v251, 16
	s_waitcnt lgkmcnt(0)
	s_nop 4
	global_load_dword v2, v1, s[8:9] sc1
	v_readlane_b32 s8, v251, 17
	v_readlane_b32 s9, v251, 18
	s_nop 4
	global_load_dword v3, v1, s[8:9] sc1
	v_readlane_b32 s8, v251, 19
	v_readlane_b32 s9, v251, 20
	s_nop 4
	global_load_dword v4, v1, s[8:9] sc1
	v_readlane_b32 s8, v251, 21
	v_readlane_b32 s9, v251, 22
	s_nop 4
	global_load_dword v5, v1, s[8:9] sc1
	v_readlane_b32 s8, v251, 23
	v_readlane_b32 s9, v251, 24
	s_nop 4
	global_load_dword v6, v1, s[8:9] sc1
	v_readlane_b32 s8, v251, 25
	v_readlane_b32 s9, v251, 26
	s_nop 4
	global_load_dword v7, v1, s[8:9] sc1
	v_readlane_b32 s8, v251, 27
	v_readlane_b32 s9, v251, 28
	s_nop 4
	global_load_dword v8, v1, s[8:9] sc1
	v_readlane_b32 s8, v251, 29
	v_readlane_b32 s9, v251, 30
	s_nop 4
	global_load_dword v9, v1, s[8:9] sc1
	v_readlane_b32 s8, v251, 31
	v_readlane_b32 s9, v251, 32
	s_nop 4
	global_load_dword v10, v1, s[8:9] sc1
	v_readlane_b32 s8, v251, 33
	v_readlane_b32 s9, v251, 34
	s_nop 4
	global_load_dword v11, v1, s[8:9] sc1
	v_readlane_b32 s8, v251, 35
	v_readlane_b32 s9, v251, 36
	s_nop 4
	global_load_dword v12, v1, s[8:9] sc1
	v_readlane_b32 s8, v251, 37
	v_readlane_b32 s9, v251, 38
	s_nop 4
	global_load_dword v13, v1, s[8:9] sc1
	v_readlane_b32 s8, v251, 39
	v_readlane_b32 s9, v251, 40
	s_nop 4
	global_load_dword v14, v1, s[8:9] sc1
	v_readlane_b32 s8, v251, 41
	v_readlane_b32 s9, v251, 42
	s_nop 4
	global_load_dword v15, v1, s[8:9] sc1
	v_readlane_b32 s8, v251, 43
	v_readlane_b32 s9, v251, 44
	s_nop 4
	global_load_dword v16, v1, s[8:9] sc1
	s_mov_b64 s[8:9], -1
	s_waitcnt vmcnt(0)
	v_add_u32_e32 v17, v2, v0
	v_add_u32_e32 v17, v17, v3
	v_add_u32_e32 v17, v17, v4
	v_add_u32_e32 v17, v17, v5
	v_add_u32_e32 v17, v17, v6
	v_add_u32_e32 v17, v17, v7
	v_add_u32_e32 v17, v17, v8
	v_add_u32_e32 v17, v17, v9
	v_add_u32_e32 v17, v17, v10
	v_add_u32_e32 v17, v17, v11
	v_add_u32_e32 v17, v17, v12
	v_add_u32_e32 v17, v17, v13
	v_add_u32_e32 v17, v17, v14
	v_add_u32_e32 v17, v17, v15
	v_add_u32_e32 v17, v17, v16
	v_cmp_eq_u32_e32 vcc, s10, v17
	s_mov_b64 s[10:11], -1
	s_cbranch_vccnz .LBB0_155
	s_and_b32 s8, s14, 0xff
	s_cmp_eq_u32 s8, 0
	s_mov_b64 s[8:9], -1
	s_mov_b64 s[12:13], -1
	s_sleep 1
	s_cbranch_scc0 .LBB0_160
	v_readlane_b32 s8, v251, 11
	v_readlane_b32 s9, v251, 12
	s_nop 4
	global_load_dword v17, v1, s[8:9] sc1
	s_waitcnt vmcnt(0)
	v_cmp_eq_u32_e32 vcc, 0, v17
	s_cbranch_vccnz .LBB0_162
	s_mov_b64 s[12:13], 0
	s_mov_b64 s[8:9], -1
